# P7 pairing v3: both WGs of a pair run the MFMA-in-SP2 flavour (unused A half neither staged nor read, vmcnt 8->6), WG c reads its A panel 128 rows lower
# speedup vs baseline: 1.0065x; 1.0065x over previous
; #define PG8_LAS __attribute__((address_space(3)))
;     __device__ __forceinline__ bool next(int i, Unit& u) const { if (i != 0) return false; u.pm = 0; u.pn = 0; return true; }
;     __device__ __forceinline__ bool next(int i, Unit& u) const { return S.next(i, u); }
; template <class Epi, class Sched, bool ALIGN_EPI = false, bool SP2 = false>
; __device__ __forceinline__ void gemm_phase(PG8_LAS unsigned char* lds, const Gemm g, const Sched& S, const Epi& E) {
;     int tid_ = my_tid();
;     const int tid = tid_, wid = __builtin_amdgcn_readfirstlane(tid >> 6), lane = tid & 63, wr = wid >> 2, wc = wid & 3, fr = lane & 15, fq = lane >> 4;
;     const int K = g.K, nt = K / BK;
;     unsigned voffA[2], voffB[2];
; #pragma unroll
;     for (int i = 0; i < 2; ++i) { int R, C; stage_rc(tid * 16 + i * 8192, R, C); const int Rb = Epi::PERM ? ((R & ~31) + perm32(R & 31)) : R;
;         voffA[i] = (unsigned)(R * g.lda + C) * 2u; voffB[i] = (unsigned)(Rb * g.ldb + C) * 2u; }
;     const size_t kstep = (size_t)(BK * 2);
;     const size_t hstepA = (size_t)HALF * g.lda * 2, hstepB = (size_t)HALF * g.ldb * 2;
;     const size_t tstepA = 2 * hstepA, tstepB = 2 * hstepB;
;     const unsigned ldsw = (unsigned)wid * 1024u;
;     const int aoff = lds_byte(wr * 64 + fr, fq * 8), boff = lds_byte(wc * 32 + fr, fq * 8);
;     ...
;     Unit cur, nxt; int ui = 0;
;     if (!S.next(0, cur)) return;
;     f32x4 acc[2][2][4][2];
; #pragma unroll
;     for (int a = 0; a < 2; ++a)
; #pragma unroll
;         for (int b = 0; b < 2; ++b)
; #pragma unroll
;             for (int m = 0; m < 4; ++m)
; #pragma unroll
;                 for (int n = 0; n < 2; ++n) acc[a][b][m][n] = (f32x4){0.f, 0.f, 0.f, 0.f};
;     bf16x8 At[4][2], B0[2][2], B1[2][2];
;     const char* cA = (const char*)g.A + (size_t)cur.pm * tstepA; const char* cB = (const char*)g.Bt + (size_t)cur.pn * tstepB;
;     ...
;         const bool has_next = S.next(ui + 1, nxt);
;         const char* nA = has_next ? (const char*)g.A + (size_t)nxt.pm * tstepA : cA; const char* nB = has_next ? (const char*)g.Bt + (size_t)nxt.pn * tstepB : cB;
.LBB0_1823:
	s_ashr_i32 s25, s24, 31
	s_lshl_b64 s[26:27], s[24:25], 20
	s_add_u32 s26, s48, s26
	s_addc_u32 s27, s49, s27
	s_cmp_eq_u32 s10, 0x100
	s_cbranch_scc0 .Lp7_noshift
	s_cmp_eq_u32 s57, 5
	s_cbranch_scc0 .Lp7_noshift
	s_cmp_lt_u32 s72, 128
	s_cbranch_scc0 .Lp7_noshift
	s_sub_u32 s26, s26, 0x80000
	s_subb_u32 s27, s27, 0
.Lp7_noshift:
	s_and_b64 s[28:29], s[36:37], exec
	s_cselect_b32 s21, s27, s31
	s_cselect_b32 s25, s26, s30
	s_ashr_i32 s23, s22, 31
	s_lshl_b64 s[28:29], s[22:23], 20
	s_add_u32 s28, s90, s28
	s_addc_u32 s29, s91, s29
	s_and_b64 s[38:39], s[36:37], exec
	s_cselect_b32 s23, s29, s35
	s_cselect_b32 s59, s28, s34
	s_add_u32 s30, s30, 0x80080
	s_addc_u32 s31, s31, 0
	s_add_u32 s60, s34, 0x100
	v_mov_b32_e32 v0, 0
	s_addc_u32 s61, s35, 0
	s_mov_b32 s62, -2
	v_mov_b32_e32 v1, v0
	v_mov_b32_e32 v2, v0
	v_mov_b32_e32 v3, v0
	v_mov_b32_e32 v8, v0
	v_mov_b32_e32 v9, v0
	v_mov_b32_e32 v10, v0
	v_mov_b32_e32 v11, v0
	v_mov_b32_e32 v16, v0
	v_mov_b32_e32 v17, v0
	v_mov_b32_e32 v18, v0
	v_mov_b32_e32 v19, v0
	v_mov_b32_e32 v24, v0
	v_mov_b32_e32 v25, v0
	v_mov_b32_e32 v26, v0
	v_mov_b32_e32 v27, v0
	v_mov_b32_e32 v32, v0
	v_mov_b32_e32 v33, v0
	v_mov_b32_e32 v34, v0
	v_mov_b32_e32 v35, v0
	v_mov_b32_e32 v40, v0
	v_mov_b32_e32 v41, v0
	v_mov_b32_e32 v42, v0
	v_mov_b32_e32 v43, v0
	v_mov_b32_e32 v48, v0
	v_mov_b32_e32 v49, v0
	v_mov_b32_e32 v50, v0
	v_mov_b32_e32 v51, v0
	v_mov_b32_e32 v56, v0
	v_mov_b32_e32 v57, v0
	v_mov_b32_e32 v58, v0
	v_mov_b32_e32 v59, v0
	v_mov_b32_e32 v4, v0
	v_mov_b32_e32 v5, v0
	v_mov_b32_e32 v6, v0
	v_mov_b32_e32 v7, v0
	v_mov_b32_e32 v12, v0
	v_mov_b32_e32 v13, v0
	v_mov_b32_e32 v14, v0
	v_mov_b32_e32 v15, v0
	v_mov_b32_e32 v20, v0
	v_mov_b32_e32 v21, v0
	v_mov_b32_e32 v22, v0
	v_mov_b32_e32 v23, v0
	v_mov_b32_e32 v28, v0
	v_mov_b32_e32 v29, v0
	v_mov_b32_e32 v30, v0
	v_mov_b32_e32 v31, v0
	v_mov_b32_e32 v36, v0
	v_mov_b32_e32 v37, v0
	v_mov_b32_e32 v38, v0
	v_mov_b32_e32 v39, v0
	v_mov_b32_e32 v44, v0
	v_mov_b32_e32 v45, v0
	v_mov_b32_e32 v46, v0
	v_mov_b32_e32 v47, v0
	v_mov_b32_e32 v52, v0
	v_mov_b32_e32 v53, v0
	v_mov_b32_e32 v54, v0
	v_mov_b32_e32 v55, v0
	v_mov_b32_e32 v60, v0
	v_mov_b32_e32 v61, v0
	v_mov_b32_e32 v62, v0
	v_mov_b32_e32 v63, v0
	v_mov_b32_e32 v64, v0
	v_mov_b32_e32 v65, v0
	v_mov_b32_e32 v66, v0
	v_mov_b32_e32 v67, v0
	v_mov_b32_e32 v72, v0
	v_mov_b32_e32 v73, v0
	v_mov_b32_e32 v74, v0
	v_mov_b32_e32 v75, v0
	v_mov_b32_e32 v80, v0
	v_mov_b32_e32 v81, v0
	v_mov_b32_e32 v82, v0
	v_mov_b32_e32 v83, v0
	v_mov_b32_e32 v88, v0
	v_mov_b32_e32 v89, v0
	v_mov_b32_e32 v90, v0
	v_mov_b32_e32 v91, v0
	v_mov_b32_e32 v96, v0
	v_mov_b32_e32 v97, v0
	v_mov_b32_e32 v98, v0
	v_mov_b32_e32 v99, v0
	v_mov_b32_e32 v104, v0
	v_mov_b32_e32 v105, v0
	v_mov_b32_e32 v106, v0
	v_mov_b32_e32 v107, v0
	v_mov_b32_e32 v112, v0
	v_mov_b32_e32 v113, v0
	v_mov_b32_e32 v114, v0
	v_mov_b32_e32 v115, v0
	v_mov_b32_e32 v120, v0
	v_mov_b32_e32 v121, v0
	v_mov_b32_e32 v122, v0
	v_mov_b32_e32 v123, v0
	v_mov_b32_e32 v68, v0
	v_mov_b32_e32 v69, v0
	v_mov_b32_e32 v70, v0
	v_mov_b32_e32 v71, v0
	v_mov_b32_e32 v76, v0
	v_mov_b32_e32 v77, v0
	v_mov_b32_e32 v78, v0
	v_mov_b32_e32 v79, v0
	v_mov_b32_e32 v84, v0
	v_mov_b32_e32 v85, v0
	v_mov_b32_e32 v86, v0
	v_mov_b32_e32 v87, v0
	v_mov_b32_e32 v92, v0
	v_mov_b32_e32 v93, v0
	v_mov_b32_e32 v94, v0
	v_mov_b32_e32 v95, v0
	v_mov_b32_e32 v100, v0
	v_mov_b32_e32 v101, v0
	v_mov_b32_e32 v102, v0
	v_mov_b32_e32 v103, v0
	v_mov_b32_e32 v108, v0
	v_mov_b32_e32 v109, v0
	v_mov_b32_e32 v110, v0
	v_mov_b32_e32 v111, v0
	v_mov_b32_e32 v116, v0
	v_mov_b32_e32 v117, v0
	v_mov_b32_e32 v118, v0
	v_mov_b32_e32 v119, v0
	v_mov_b32_e32 v124, v0
	v_mov_b32_e32 v125, v0
	v_mov_b32_e32 v126, v0
	v_mov_b32_e32 v127, v0
	s_cmp_eq_u32 s57, 6
	s_cbranch_scc0 .Lp7_full_loop
	s_cmp_eq_u32 s10, 0x100
	s_cbranch_scc1 .Lp7h_loop

;     __device__ __forceinline__ void operator()(const f32x4 (&acc)[2][2][4][2], const Unit& u, int wr, int wc, int fr, int fq) const {
;     ...
; #pragma unroll
;         for (int ai = 0; ai < 2; ++ai)
; #pragma unroll
;             for (int m = 0; m < 4; ++m) { const size_t row = (size_t)u.pm * BM + ai * HALF + wr * 64 + m * 16 + fr;
;                 const float rs = tab[ai * HALF + wr * 64 + m * 16 + fr];
.LBB0_1833:
	s_ashr_i32 s21, s20, 31
	s_lshl_b64 s[20:21], s[20:21], 8
	s_add_u32 s20, s20, s43
	s_addc_u32 s21, s21, s51
	v_ashrrev_i32_e32 v145, 31, v144
	v_lshl_add_u32 v155, v144, 2, s52
	v_lshl_add_u64 v[146:147], s[20:21], 0, v[144:145]
	v_lshlrev_b32_e32 v144, 3, v156
	s_cmp_eq_u32 s57, 6
	s_cbranch_scc0 .Lp7_epi_full
	s_cmp_eq_u32 s10, 0x100
	s_cbranch_scc1 .Lp7_h_epi

; __device__ __forceinline__ float sigmoidf_(float x) { return __builtin_amdgcn_rcpf(1.0f + __expf(-x)); }
; __device__ __forceinline__ u32x4 pack8(const f32x4& a, const f32x4& b) { u32x4 w; w.x = cvt_pk_bf16(a[0], a[1]); w.y = cvt_pk_bf16(a[2], a[3]); w.z = cvt_pk_bf16(b[0], b[1]); w.w = cvt_pk_bf16(b[2], b[3]); return w; }
;     __device__ __forceinline__ void operator()(const f32x4 (&acc)[2][2][4][2], const Unit& u, int wr, int wc, int fr, int fq) const {
;     ...
; #pragma unroll
;         for (int ai = 0; ai < 2; ++ai)
; #pragma unroll
;             for (int m = 0; m < 4; ++m) { const size_t row = (size_t)u.pm * BM + ai * HALF + wr * 64 + m * 16 + fr;
;                 const float rs = tab[ai * HALF + wr * 64 + m * 16 + fr];
;                 f32x4 h[2];
; #pragma unroll
;                 for (int n = 0; n < 2; ++n) { const f32x4 g = acc[ai][0][m][n] * rs, up = acc[ai][1][m][n] * rs;
; #pragma unroll
;                     for (int j = 0; j < 4; ++j) h[n][j] = g[j] * sigmoidf_(g[j]) * up[j]; }
;                 *(u32x4*)(H + row * 5632 + u.pn * HALF + wc * 32 + fq * 8) = pack8(h[0], h[1]); }
.Lp7_blk4:
	ds_read_b32 v64, v155 offset:512
	s_nop 0
	v_mov_b32_e32 v66, v56
	v_mov_b32_e32 v67, v60
	v_mov_b32_e32 v60, v57
	s_waitcnt lgkmcnt(0)
	v_pk_mul_f32 v[66:67], v[66:67], v[64:65] op_sel_hi:[1,0]
	s_nop 0
	v_mul_f32_e32 v56, 0xbfb8aa3b, v67
	v_exp_f32_e32 v56, v56
	s_nop 0
	v_add_f32_e32 v56, 1.0, v56
	v_rcp_f32_e32 v56, v56
	s_nop 0
	v_mul_f32_e32 v56, v67, v56
	v_mul_f32_e32 v65, v66, v56
	v_pk_mul_f32 v[56:57], v[60:61], v[64:65] op_sel_hi:[1,0]
	s_nop 0
	v_mul_f32_e32 v60, 0xbfb8aa3b, v57
	v_exp_f32_e32 v60, v60
	s_nop 0
	v_add_f32_e32 v60, 1.0, v60
	v_rcp_f32_e32 v60, v60
	s_nop 0
	v_mul_f32_e32 v57, v57, v60
	v_mul_f32_e32 v60, v56, v57
	v_mov_b32_e32 v56, v58
	v_mov_b32_e32 v57, v62
	v_pk_mul_f32 v[56:57], v[56:57], v[64:65] op_sel_hi:[1,0]
	v_mov_b32_e32 v62, v59
	v_mul_f32_e32 v58, 0xbfb8aa3b, v57
	v_exp_f32_e32 v58, v58
	s_nop 0
	v_add_f32_e32 v58, 1.0, v58
	v_rcp_f32_e32 v58, v58
	s_nop 0
	v_mul_f32_e32 v57, v57, v58
	v_mul_f32_e32 v58, v56, v57
	v_pk_mul_f32 v[56:57], v[62:63], v[64:65] op_sel_hi:[1,0]
	s_nop 0
	v_mul_f32_e32 v59, 0xbfb8aa3b, v57
	v_exp_f32_e32 v59, v59
	s_nop 0
	v_add_f32_e32 v59, 1.0, v59
	v_rcp_f32_e32 v59, v59
	s_nop 0
	v_mul_f32_e32 v57, v57, v59
	v_mul_f32_e32 v59, v56, v57
	v_mov_b32_e32 v56, v48
	v_mov_b32_e32 v57, v52
	v_pk_mul_f32 v[56:57], v[56:57], v[64:65] op_sel_hi:[1,0]
	v_mov_b32_e32 v52, v49
	v_mul_f32_e32 v48, 0xbfb8aa3b, v57
	v_exp_f32_e32 v48, v48
	s_nop 0
	v_add_f32_e32 v48, 1.0, v48
	v_rcp_f32_e32 v48, v48
	s_nop 0
	v_mul_f32_e32 v48, v57, v48
	v_mul_f32_e32 v56, v56, v48
	v_pk_mul_f32 v[48:49], v[52:53], v[64:65] op_sel_hi:[1,0]
	s_nop 0
	v_mul_f32_e32 v52, 0xbfb8aa3b, v49
	v_exp_f32_e32 v52, v52
	s_nop 0
	v_add_f32_e32 v52, 1.0, v52
	v_rcp_f32_e32 v52, v52
	s_nop 0
	v_mul_f32_e32 v49, v49, v52
	v_mul_f32_e32 v52, v48, v49
	v_mov_b32_e32 v48, v50
	v_mov_b32_e32 v49, v54
	v_pk_mul_f32 v[48:49], v[48:49], v[64:65] op_sel_hi:[1,0]
	v_mov_b32_e32 v54, v51
	v_mul_f32_e32 v50, 0xbfb8aa3b, v49
	v_exp_f32_e32 v50, v50
	s_nop 0
	v_add_f32_e32 v50, 1.0, v50
	v_rcp_f32_e32 v50, v50
	s_nop 0
	v_mul_f32_e32 v49, v49, v50
	v_mul_f32_e32 v53, v48, v49
	v_pk_mul_f32 v[48:49], v[54:55], v[64:65] op_sel_hi:[1,0]
	s_nop 0
	v_mul_f32_e32 v50, 0xbfb8aa3b, v49
	v_exp_f32_e32 v50, v50
	s_nop 0
	v_add_f32_e32 v50, 1.0, v50
	v_rcp_f32_e32 v50, v50
	s_nop 0
	v_mul_f32_e32 v49, v49, v50
	v_mul_f32_e32 v51, v48, v49
	v_cvt_pk_bf16_f32 v48, v65, v60
	v_cvt_pk_bf16_f32 v49, v58, v59
	v_cvt_pk_bf16_f32 v50, v56, v52
	v_add_co_u32_e32 v52, vcc, s20, v112
	v_cvt_pk_bf16_f32 v51, v53, v51
	s_mov_b32 s20, 0x18c000
	s_nop 0
	v_addc_co_u32_e32 v53, vcc, 0, v113, vcc
	global_store_dwordx4 v[52:53], v[48:51], off
	ds_read_b32 v48, v155 offset:576
	s_nop 0
	v_mov_b32_e32 v50, v40
	v_mov_b32_e32 v51, v44
	v_mov_b32_e32 v44, v41
	s_waitcnt lgkmcnt(0)
	v_pk_mul_f32 v[50:51], v[50:51], v[48:49] op_sel_hi:[1,0]
	s_nop 0
	v_mul_f32_e32 v40, 0xbfb8aa3b, v51
	v_exp_f32_e32 v40, v40
	s_nop 0
	v_add_f32_e32 v40, 1.0, v40
	v_rcp_f32_e32 v40, v40
	s_nop 0
	v_mul_f32_e32 v40, v51, v40
	v_mul_f32_e32 v49, v50, v40
	v_pk_mul_f32 v[40:41], v[44:45], v[48:49] op_sel_hi:[1,0]
	s_nop 0
	v_mul_f32_e32 v44, 0xbfb8aa3b, v41
	v_exp_f32_e32 v44, v44
	s_nop 0
	v_add_f32_e32 v44, 1.0, v44
	v_rcp_f32_e32 v44, v44
	s_nop 0
	v_mul_f32_e32 v41, v41, v44
	v_mul_f32_e32 v44, v40, v41
	v_mov_b32_e32 v40, v42
	v_mov_b32_e32 v41, v46
	v_pk_mul_f32 v[40:41], v[40:41], v[48:49] op_sel_hi:[1,0]
	v_mov_b32_e32 v46, v43
	v_mul_f32_e32 v42, 0xbfb8aa3b, v41
	v_exp_f32_e32 v42, v42
	s_nop 0
	v_add_f32_e32 v42, 1.0, v42
	v_rcp_f32_e32 v42, v42
	s_nop 0
	v_mul_f32_e32 v41, v41, v42
	v_mul_f32_e32 v42, v40, v41
	v_pk_mul_f32 v[40:41], v[46:47], v[48:49] op_sel_hi:[1,0]
	s_nop 0
	v_mul_f32_e32 v43, 0xbfb8aa3b, v41
	v_exp_f32_e32 v43, v43
	s_nop 0
	v_add_f32_e32 v43, 1.0, v43
	v_rcp_f32_e32 v43, v43
	s_nop 0
	v_mul_f32_e32 v41, v41, v43
	v_mul_f32_e32 v43, v40, v41
	v_mov_b32_e32 v40, v32
	v_mov_b32_e32 v41, v36
	v_pk_mul_f32 v[40:41], v[40:41], v[48:49] op_sel_hi:[1,0]
	v_mov_b32_e32 v36, v33
	v_mul_f32_e32 v32, 0xbfb8aa3b, v41
	v_exp_f32_e32 v32, v32
	s_nop 0
	v_add_f32_e32 v32, 1.0, v32
	v_rcp_f32_e32 v32, v32
	s_nop 0
	v_mul_f32_e32 v32, v41, v32
	v_mul_f32_e32 v40, v40, v32
	v_pk_mul_f32 v[32:33], v[36:37], v[48:49] op_sel_hi:[1,0]
	s_nop 0
	v_mul_f32_e32 v36, 0xbfb8aa3b, v33
	v_exp_f32_e32 v36, v36
	s_nop 0
	v_add_f32_e32 v36, 1.0, v36
	v_rcp_f32_e32 v36, v36
	s_nop 0
	v_mul_f32_e32 v33, v33, v36
	v_mul_f32_e32 v36, v32, v33
	v_mov_b32_e32 v32, v34
	v_mov_b32_e32 v33, v38
	v_pk_mul_f32 v[32:33], v[32:33], v[48:49] op_sel_hi:[1,0]
	v_mov_b32_e32 v38, v35
	v_mul_f32_e32 v34, 0xbfb8aa3b, v33
	v_exp_f32_e32 v34, v34
	s_nop 0
	v_add_f32_e32 v34, 1.0, v34
	v_rcp_f32_e32 v34, v34
	s_nop 0
	v_mul_f32_e32 v33, v33, v34
	v_mul_f32_e32 v37, v32, v33
	v_pk_mul_f32 v[32:33], v[38:39], v[48:49] op_sel_hi:[1,0]
	s_nop 0
	v_mul_f32_e32 v34, 0xbfb8aa3b, v33
	v_exp_f32_e32 v34, v34
	s_nop 0
	v_add_f32_e32 v34, 1.0, v34
	v_rcp_f32_e32 v34, v34
	s_nop 0
	v_mul_f32_e32 v33, v33, v34
	v_mul_f32_e32 v35, v32, v33
	v_cvt_pk_bf16_f32 v32, v49, v44
	v_cvt_pk_bf16_f32 v33, v42, v43
	v_cvt_pk_bf16_f32 v34, v40, v36
	v_add_co_u32_e32 v36, vcc, s20, v112
	v_cvt_pk_bf16_f32 v35, v37, v35
	s_mov_b32 s20, 0x1b8000
	s_nop 0
	v_addc_co_u32_e32 v37, vcc, 0, v113, vcc
	global_store_dwordx4 v[36:37], v[32:35], off
	ds_read_b32 v32, v155 offset:640
	s_nop 0
	v_mov_b32_e32 v34, v24
	v_mov_b32_e32 v35, v28
	v_mov_b32_e32 v28, v25
	s_waitcnt lgkmcnt(0)
; __device__ __forceinline__ float sigmoidf_(float x) { return __builtin_amdgcn_rcpf(1.0f + __expf(-x)); }
; __device__ __forceinline__ u32x4 pack8(const f32x4& a, const f32x4& b) { u32x4 w; w.x = cvt_pk_bf16(a[0], a[1]); w.y = cvt_pk_bf16(a[2], a[3]); w.z = cvt_pk_bf16(b[0], b[1]); w.w = cvt_pk_bf16(b[2], b[3]); return w; }
;     __device__ __forceinline__ void operator()(const f32x4 (&acc)[2][2][4][2], const Unit& u, int wr, int wc, int fr, int fq) const {
;     ...
; #pragma unroll
;         for (int ai = 0; ai < 2; ++ai)
; #pragma unroll
;             for (int m = 0; m < 4; ++m) { const size_t row = (size_t)u.pm * BM + ai * HALF + wr * 64 + m * 16 + fr;
;                 const float rs = tab[ai * HALF + wr * 64 + m * 16 + fr];
;                 f32x4 h[2];
; #pragma unroll
;                 for (int n = 0; n < 2; ++n) { const f32x4 g = acc[ai][0][m][n] * rs, up = acc[ai][1][m][n] * rs;
; #pragma unroll
;                     for (int j = 0; j < 4; ++j) h[n][j] = g[j] * sigmoidf_(g[j]) * up[j]; }
;                 *(u32x4*)(H + row * 5632 + u.pn * HALF + wc * 32 + fq * 8) = pack8(h[0], h[1]); }
; template <class Epi, class Sched, bool ALIGN_EPI = false, bool SP2 = false>
; __device__ __forceinline__ void gemm_phase(PG8_LAS unsigned char* lds, const Gemm g, const Sched& S, const Epi& E) {
;     ...
;         if constexpr (!Epi::AFTER_DRAIN) { E(acc, cur, wr, wc, fr, fq); S.done(cur); }
;         if (!has_next) break;
	v_pk_mul_f32 v[34:35], v[34:35], v[32:33] op_sel_hi:[1,0]
	s_nop 0
	v_mul_f32_e32 v24, 0xbfb8aa3b, v35
	v_exp_f32_e32 v24, v24
	s_nop 0
	v_add_f32_e32 v24, 1.0, v24
	v_rcp_f32_e32 v24, v24
	s_nop 0
	v_mul_f32_e32 v24, v35, v24
	v_mul_f32_e32 v33, v34, v24
	v_pk_mul_f32 v[24:25], v[28:29], v[32:33] op_sel_hi:[1,0]
	s_nop 0
	v_mul_f32_e32 v28, 0xbfb8aa3b, v25
	v_exp_f32_e32 v28, v28
	s_nop 0
	v_add_f32_e32 v28, 1.0, v28
	v_rcp_f32_e32 v28, v28
	s_nop 0
	v_mul_f32_e32 v25, v25, v28
	v_mul_f32_e32 v28, v24, v25
	v_mov_b32_e32 v24, v26
	v_mov_b32_e32 v25, v30
	v_pk_mul_f32 v[24:25], v[24:25], v[32:33] op_sel_hi:[1,0]
	v_mov_b32_e32 v30, v27
	v_mul_f32_e32 v26, 0xbfb8aa3b, v25
	v_exp_f32_e32 v26, v26
	s_nop 0
	v_add_f32_e32 v26, 1.0, v26
	v_rcp_f32_e32 v26, v26
	s_nop 0
	v_mul_f32_e32 v25, v25, v26
	v_mul_f32_e32 v26, v24, v25
	v_pk_mul_f32 v[24:25], v[30:31], v[32:33] op_sel_hi:[1,0]
	s_nop 0
	v_mul_f32_e32 v27, 0xbfb8aa3b, v25
	v_exp_f32_e32 v27, v27
	s_nop 0
	v_add_f32_e32 v27, 1.0, v27
	v_rcp_f32_e32 v27, v27
	s_nop 0
	v_mul_f32_e32 v25, v25, v27
	v_mul_f32_e32 v27, v24, v25
	v_mov_b32_e32 v24, v16
	v_mov_b32_e32 v25, v20
	v_pk_mul_f32 v[24:25], v[24:25], v[32:33] op_sel_hi:[1,0]
	v_mov_b32_e32 v20, v17
	v_mul_f32_e32 v16, 0xbfb8aa3b, v25
	v_exp_f32_e32 v16, v16
	s_nop 0
	v_add_f32_e32 v16, 1.0, v16
	v_rcp_f32_e32 v16, v16
	s_nop 0
	v_mul_f32_e32 v16, v25, v16
	v_mul_f32_e32 v24, v24, v16
	v_pk_mul_f32 v[16:17], v[20:21], v[32:33] op_sel_hi:[1,0]
	s_nop 0
	v_mul_f32_e32 v20, 0xbfb8aa3b, v17
	v_exp_f32_e32 v20, v20
	s_nop 0
	v_add_f32_e32 v20, 1.0, v20
	v_rcp_f32_e32 v20, v20
	s_nop 0
	v_mul_f32_e32 v17, v17, v20
	v_mul_f32_e32 v20, v16, v17
	v_mov_b32_e32 v16, v18
	v_mov_b32_e32 v17, v22
	v_pk_mul_f32 v[16:17], v[16:17], v[32:33] op_sel_hi:[1,0]
	v_mov_b32_e32 v22, v19
	v_mul_f32_e32 v18, 0xbfb8aa3b, v17
	v_exp_f32_e32 v18, v18
	s_nop 0
	v_add_f32_e32 v18, 1.0, v18
	v_rcp_f32_e32 v18, v18
	s_nop 0
	v_mul_f32_e32 v17, v17, v18
	v_mul_f32_e32 v21, v16, v17
	v_pk_mul_f32 v[16:17], v[22:23], v[32:33] op_sel_hi:[1,0]
	s_nop 0
	v_mul_f32_e32 v18, 0xbfb8aa3b, v17
	v_exp_f32_e32 v18, v18
	s_nop 0
	v_add_f32_e32 v18, 1.0, v18
	v_rcp_f32_e32 v18, v18
	s_nop 0
	v_mul_f32_e32 v17, v17, v18
	v_mul_f32_e32 v19, v16, v17
	v_cvt_pk_bf16_f32 v16, v33, v28
	v_cvt_pk_bf16_f32 v17, v26, v27
	v_cvt_pk_bf16_f32 v18, v24, v20
	v_add_co_u32_e32 v20, vcc, s20, v112
	v_cvt_pk_bf16_f32 v19, v21, v19
	s_mov_b64 s[20:21], -1
	s_nop 0
	v_addc_co_u32_e32 v21, vcc, 0, v113, vcc
	global_store_dwordx4 v[20:21], v[16:19], off
	ds_read_b32 v16, v155 offset:704
	s_nop 0
	v_mov_b32_e32 v18, v8
	v_mov_b32_e32 v19, v12
	v_mov_b32_e32 v12, v9
	s_waitcnt lgkmcnt(0)
	v_pk_mul_f32 v[18:19], v[18:19], v[16:17] op_sel_hi:[1,0]
	s_nop 0
	v_mul_f32_e32 v8, 0xbfb8aa3b, v19
	v_exp_f32_e32 v8, v8
	s_nop 0
	v_add_f32_e32 v8, 1.0, v8
	v_rcp_f32_e32 v8, v8
	s_nop 0
	v_mul_f32_e32 v8, v19, v8
	v_mul_f32_e32 v17, v18, v8
	v_pk_mul_f32 v[8:9], v[12:13], v[16:17] op_sel_hi:[1,0]
	s_nop 0
	v_mul_f32_e32 v12, 0xbfb8aa3b, v9
	v_exp_f32_e32 v12, v12
	s_nop 0
	v_add_f32_e32 v12, 1.0, v12
	v_rcp_f32_e32 v12, v12
	s_nop 0
	v_mul_f32_e32 v9, v9, v12
	v_mul_f32_e32 v12, v8, v9
	v_mov_b32_e32 v8, v10
	v_mov_b32_e32 v9, v14
	v_pk_mul_f32 v[8:9], v[8:9], v[16:17] op_sel_hi:[1,0]
	v_mov_b32_e32 v14, v11
	v_mul_f32_e32 v10, 0xbfb8aa3b, v9
	v_exp_f32_e32 v10, v10
	s_nop 0
	v_add_f32_e32 v10, 1.0, v10
	v_rcp_f32_e32 v10, v10
	s_nop 0
	v_mul_f32_e32 v9, v9, v10
	v_mul_f32_e32 v10, v8, v9
	v_pk_mul_f32 v[8:9], v[14:15], v[16:17] op_sel_hi:[1,0]
	s_nop 0
	v_mul_f32_e32 v11, 0xbfb8aa3b, v9
	v_exp_f32_e32 v11, v11
	s_nop 0
	v_add_f32_e32 v11, 1.0, v11
	v_rcp_f32_e32 v11, v11
	s_nop 0
	v_mul_f32_e32 v9, v9, v11
	v_mul_f32_e32 v11, v8, v9
	v_mov_b32_e32 v8, v0
	v_mov_b32_e32 v9, v4
	v_pk_mul_f32 v[8:9], v[8:9], v[16:17] op_sel_hi:[1,0]
	v_mov_b32_e32 v4, v1
	v_mul_f32_e32 v0, 0xbfb8aa3b, v9
	v_exp_f32_e32 v0, v0
	s_nop 0
	v_add_f32_e32 v0, 1.0, v0
	v_rcp_f32_e32 v0, v0
	s_nop 0
	v_mul_f32_e32 v0, v9, v0
	v_mul_f32_e32 v8, v8, v0
	v_pk_mul_f32 v[0:1], v[4:5], v[16:17] op_sel_hi:[1,0]
	s_nop 0
	v_mul_f32_e32 v4, 0xbfb8aa3b, v1
	v_exp_f32_e32 v4, v4
	s_nop 0
	v_add_f32_e32 v4, 1.0, v4
	v_rcp_f32_e32 v4, v4
	s_nop 0
	v_mul_f32_e32 v1, v1, v4
	v_mul_f32_e32 v4, v0, v1
	v_mov_b32_e32 v0, v2
	v_mov_b32_e32 v1, v6
	v_pk_mul_f32 v[0:1], v[0:1], v[16:17] op_sel_hi:[1,0]
	v_mov_b32_e32 v6, v3
	v_mul_f32_e32 v2, 0xbfb8aa3b, v1
	v_exp_f32_e32 v2, v2
	s_nop 0
	v_add_f32_e32 v2, 1.0, v2
	v_rcp_f32_e32 v2, v2
	s_nop 0
	v_mul_f32_e32 v1, v1, v2
	v_mul_f32_e32 v5, v0, v1
	v_pk_mul_f32 v[0:1], v[6:7], v[16:17] op_sel_hi:[1,0]
	s_nop 0
	v_mul_f32_e32 v2, 0xbfb8aa3b, v1
	v_exp_f32_e32 v2, v2
	s_nop 0
	v_add_f32_e32 v2, 1.0, v2
	v_rcp_f32_e32 v2, v2
	s_nop 0
	v_mul_f32_e32 v1, v1, v2
	v_mul_f32_e32 v3, v0, v1
	v_cvt_pk_bf16_f32 v0, v17, v12
	v_cvt_pk_bf16_f32 v1, v10, v11
	v_cvt_pk_bf16_f32 v2, v8, v4
	v_add_co_u32_e32 v4, vcc, 0x1e4000, v112
	v_cvt_pk_bf16_f32 v3, v5, v3
	s_nop 1
	v_addc_co_u32_e32 v5, vcc, 0, v113, vcc
	s_andn2_b64 vcc, exec, s[36:37]
	global_store_dwordx4 v[4:5], v[0:3], off
	s_cbranch_vccnz .LBB0_1820
	s_andn2_b64 vcc, exec, s[14:15]
	s_cbranch_vccnz .LBB0_1819
	s_barrier
	s_branch .LBB0_1819
; #define PG8_STAGE(bufoff, gbase, voff) do { _Pragma("unroll") for (int _i = 0; _i < 2; ++_i) \
;         __builtin_amdgcn_global_load_lds((const unsigned*)((const char*)(gbase) + (voff)[_i]), (PG8_LAS unsigned*)(lds + (bufoff) + ldsw + _i * 8192), 16, 0, 0); } while (0)
; #define PG8_LDA(dst, b, h) do { _Pragma("unroll") for (int m = 0; m < 4; ++m) _Pragma("unroll") for (int k = 0; k < 2; ++k) dst[m][k] = *(const PG8_LAS bf16x8*)(lds + PG8_SA(b, h) + aoff + m * 2048 + k * 1024); } while (0)
; #define PG8_LDB(dst, b, h) do { _Pragma("unroll") for (int n = 0; n < 2; ++n) _Pragma("unroll") for (int k = 0; k < 2; ++k) dst[n][k] = *(const PG8_LAS bf16x8*)(lds + PG8_SB(b, h) + boff + n * 2048 + k * 1024); } while (0)
; #define PG8_MMA(ai, bj, At, Bt) do { __builtin_amdgcn_s_setprio(1); _Pragma("unroll") for (int m = 0; m < 4; ++m) _Pragma("unroll") for (int n = 0; n < 2; ++n) _Pragma("unroll") for (int k = 0; k < 2; ++k) \
;         acc[ai][bj][m][n] = __builtin_amdgcn_mfma_f32_16x16x32_bf16(Bt[n][k], At[m][k], acc[ai][bj][m][n], 0, 0, 0); __builtin_amdgcn_s_setprio(0); } while (0)
; #define PG8_WAIT_V(n) asm volatile("s_waitcnt vmcnt(" #n ")" ::: "memory")
; #define PG8_WAIT_L(n) asm volatile("s_waitcnt lgkmcnt(" #n ")" ::: "memory")
; #define PG8_BAR __builtin_amdgcn_s_barrier()
; #define PG8_SCHED __builtin_amdgcn_sched_barrier(0)
; template <class Epi, class Sched, bool ALIGN_EPI = false, bool SP2 = false>
; __device__ __forceinline__ void gemm_phase(PG8_LAS unsigned char* lds, const Gemm g, const Sched& S, const Epi& E) {
;     ...
;             PG8_LDB(B0, 0, 0); PG8_LDB(B1, 0, 1); PG8_SCHED; PG8_LDA(At, 0, 0); PG8_STAGE(PG8_SA(1, 1), a1 + hstepA, voffA);
;             PG8_WAIT_V(8); PG8_WAIT_L(0); PG8_BAR; PG8_MMA(0, 0, At, B0); PG8_MMA(0, 1, At, B1); PG8_BAR; PG8_SCHED;
;             PG8_LDA(At, 0, 1); PG8_STAGE(PG8_SB(0, 0), b2, voffB); PG8_STAGE(PG8_SB(0, 1), b2 + hstepB, voffB); PG8_STAGE(PG8_SA(0, 0), a2, voffA);
;             PG8_WAIT_V(8); PG8_WAIT_L(0); PG8_BAR; PG8_MMA(1, 0, At, B0); PG8_MMA(1, 1, At, B1); PG8_BAR; PG8_SCHED;
;             PG8_LDB(B0, 1, 0); PG8_LDB(B1, 1, 1); PG8_SCHED; PG8_LDA(At, 1, 0); PG8_STAGE(PG8_SA(0, 1), a2 + hstepA, voffA);
;             PG8_WAIT_V(8); PG8_WAIT_L(0); PG8_BAR; PG8_MMA(0, 0, At, B0); PG8_MMA(0, 1, At, B1); PG8_BAR; PG8_SCHED;
.Lp7h_loop:
	ds_read_b128 v[144:147], v151
	ds_read_b128 v[156:159], v151 offset:1024
	ds_read_b128 v[160:163], v151 offset:2048
	ds_read_b128 v[164:167], v151 offset:3072
	ds_read_b128 v[168:171], v152
	ds_read_b128 v[172:175], v152 offset:1024
	ds_read_b128 v[176:179], v152 offset:2048
	ds_read_b128 v[180:183], v152 offset:3072
	s_add_u32 s34, s30, 0xfff80080
	s_addc_u32 s35, s31, -1
	s_cmp_eq_u32 s62, 28
	s_cselect_b32 s39, s21, s35
	s_cselect_b32 s38, s25, s34
	s_cselect_b32 s35, s23, s61
	s_cselect_b32 s34, s59, s60
	v_lshl_add_u64 v[216:217], s[30:31], 0, v[136:137]
	s_add_i32 m0, s6, 0xc000
	global_load_lds_dwordx4 v[216:217], off
	v_lshl_add_u64 v[216:217], s[30:31], 0, v[138:139]
	s_add_i32 m0, s6, 0xe000
	s_nop 0
	global_load_lds_dwordx4 v[216:217], off
	s_waitcnt vmcnt(6)
	s_waitcnt lgkmcnt(0)
	s_barrier
	s_setprio 1
	s_waitcnt lgkmcnt(0)
	s_setprio 0
	s_setprio 1
	s_setprio 0
	s_barrier
	s_add_i32 s63, s53, s4
	v_lshl_add_u64 v[216:217], s[34:35], 0, v[132:133]
	s_mov_b32 m0, s63
	ds_read_b128 v[184:187], v153 offset:16384
	ds_read_b128 v[188:191], v153 offset:17408
	ds_read_b128 v[192:195], v153 offset:18432
	ds_read_b128 v[196:199], v153 offset:19456
	ds_read_b128 v[200:203], v153 offset:20480
	ds_read_b128 v[204:207], v153 offset:21504
	ds_read_b128 v[208:211], v153 offset:22528
	ds_read_b128 v[212:215], v153 offset:23552
	global_load_lds_dwordx4 v[216:217], off
	s_add_i32 m0, s63, 0x2000
	s_add_u32 s64, s34, 0x80000
	v_lshl_add_u64 v[218:219], s[34:35], 0, v[128:129]
	s_addc_u32 s65, s35, 0
	s_add_i32 s63, s54, s4
	global_load_lds_dwordx4 v[218:219], off
	v_lshl_add_u64 v[220:221], s[64:65], 0, v[132:133]
	s_mov_b32 m0, s63
	v_lshl_add_u64 v[222:223], s[38:39], 0, v[130:131]
	global_load_lds_dwordx4 v[220:221], off
	v_lshl_add_u64 v[220:221], s[64:65], 0, v[128:129]
	s_add_i32 m0, s63, 0x2000
	s_nop 0
	global_load_lds_dwordx4 v[220:221], off
	v_lshl_add_u64 v[220:221], s[38:39], 0, v[134:135]
	s_mov_b32 m0, s6
	s_nop 0
	s_mov_b32 m0, s7
	s_nop 0
	s_waitcnt vmcnt(6)
	s_waitcnt lgkmcnt(0)
	s_barrier
	s_setprio 1
	s_waitcnt lgkmcnt(0)
	v_mfma_f32_16x16x32_bf16 v[60:63], v[144:147], v[184:187], v[60:63]
	v_mfma_f32_16x16x32_bf16 v[52:55], v[160:163], v[184:187], v[52:55]
	v_mfma_f32_16x16x32_bf16 v[44:47], v[144:147], v[192:195], v[44:47]
	v_mfma_f32_16x16x32_bf16 v[36:39], v[160:163], v[192:195], v[36:39]
	v_mfma_f32_16x16x32_bf16 v[28:31], v[144:147], v[200:203], v[28:31]
	v_mfma_f32_16x16x32_bf16 v[20:23], v[160:163], v[200:203], v[20:23]
	v_mfma_f32_16x16x32_bf16 v[12:15], v[144:147], v[208:211], v[12:15]
	v_mfma_f32_16x16x32_bf16 v[4:7], v[160:163], v[208:211], v[4:7]
	v_mfma_f32_16x16x32_bf16 v[60:63], v[156:159], v[188:191], v[60:63]
	v_mfma_f32_16x16x32_bf16 v[52:55], v[164:167], v[188:191], v[52:55]
	v_mfma_f32_16x16x32_bf16 v[44:47], v[156:159], v[196:199], v[44:47]
	v_mfma_f32_16x16x32_bf16 v[36:39], v[164:167], v[196:199], v[36:39]
	v_mfma_f32_16x16x32_bf16 v[28:31], v[156:159], v[204:207], v[28:31]
	v_mfma_f32_16x16x32_bf16 v[20:23], v[164:167], v[204:207], v[20:23]
	v_mfma_f32_16x16x32_bf16 v[12:15], v[156:159], v[212:215], v[12:15]
	v_mfma_f32_16x16x32_bf16 v[4:7], v[164:167], v[212:215], v[4:7]
	s_setprio 0
	s_setprio 1
	v_mfma_f32_16x16x32_bf16 v[56:59], v[168:171], v[184:187], v[56:59]
	v_mfma_f32_16x16x32_bf16 v[48:51], v[176:179], v[184:187], v[48:51]
	v_mfma_f32_16x16x32_bf16 v[40:43], v[168:171], v[192:195], v[40:43]
	v_mfma_f32_16x16x32_bf16 v[32:35], v[176:179], v[192:195], v[32:35]
	v_mfma_f32_16x16x32_bf16 v[24:27], v[168:171], v[200:203], v[24:27]
	v_mfma_f32_16x16x32_bf16 v[16:19], v[176:179], v[200:203], v[16:19]
	v_mfma_f32_16x16x32_bf16 v[8:11], v[168:171], v[208:211], v[8:11]
	v_mfma_f32_16x16x32_bf16 v[0:3], v[176:179], v[208:211], v[0:3]
	v_mfma_f32_16x16x32_bf16 v[56:59], v[172:175], v[188:191], v[56:59]
	v_mfma_f32_16x16x32_bf16 v[48:51], v[180:183], v[188:191], v[48:51]
	v_mfma_f32_16x16x32_bf16 v[40:43], v[172:175], v[196:199], v[40:43]
	v_mfma_f32_16x16x32_bf16 v[32:35], v[180:183], v[196:199], v[32:35]
	v_mfma_f32_16x16x32_bf16 v[24:27], v[172:175], v[204:207], v[24:27]
	v_mfma_f32_16x16x32_bf16 v[16:19], v[180:183], v[204:207], v[16:19]
	v_mfma_f32_16x16x32_bf16 v[8:11], v[172:175], v[212:215], v[8:11]
	v_mfma_f32_16x16x32_bf16 v[0:3], v[180:183], v[212:215], v[0:3]
	s_setprio 0
	s_barrier
	s_add_i32 s63, 0, 0x18000
	v_add_u32_e32 v155, s63, v150
	s_add_i32 s64, 0, 0x1c000
	ds_read_b128 v[144:147], v155
	ds_read_b128 v[156:159], v155 offset:1024
	ds_read_b128 v[160:163], v155 offset:2048
	ds_read_b128 v[164:167], v155 offset:3072
	v_add_u32_e32 v155, s64, v150
	ds_read_b128 v[168:171], v155
	ds_read_b128 v[172:175], v155 offset:1024
	ds_read_b128 v[176:179], v155 offset:2048
	ds_read_b128 v[180:183], v155 offset:3072
	s_add_u32 s38, s38, 0x80000
	s_addc_u32 s39, s39, 0
	s_mov_b32 m0, s41
	v_lshl_add_u64 v[224:225], s[38:39], 0, v[134:135]
	global_load_lds_dwordx4 v[224:225], off
	v_lshl_add_u64 v[224:225], s[38:39], 0, v[130:131]
	s_mov_b32 m0, s42
	s_nop 0
	global_load_lds_dwordx4 v[224:225], off
	s_waitcnt vmcnt(6)
	s_waitcnt lgkmcnt(0)
	s_barrier
; __device__ __forceinline__ float sigmoidf_(float x) { return __builtin_amdgcn_rcpf(1.0f + __expf(-x)); }
; __device__ __forceinline__ u32x4 pack8(const f32x4& a, const f32x4& b) { u32x4 w; w.x = cvt_pk_bf16(a[0], a[1]); w.y = cvt_pk_bf16(a[2], a[3]); w.z = cvt_pk_bf16(b[0], b[1]); w.w = cvt_pk_bf16(b[2], b[3]); return w; }
; #define PG8_STAGE(bufoff, gbase, voff) do { _Pragma("unroll") for (int _i = 0; _i < 2; ++_i) \
;         __builtin_amdgcn_global_load_lds((const unsigned*)((const char*)(gbase) + (voff)[_i]), (PG8_LAS unsigned*)(lds + (bufoff) + ldsw + _i * 8192), 16, 0, 0); } while (0)
; #define PG8_LDA(dst, b, h) do { _Pragma("unroll") for (int m = 0; m < 4; ++m) _Pragma("unroll") for (int k = 0; k < 2; ++k) dst[m][k] = *(const PG8_LAS bf16x8*)(lds + PG8_SA(b, h) + aoff + m * 2048 + k * 1024); } while (0)
; #define PG8_MMA(ai, bj, At, Bt) do { __builtin_amdgcn_s_setprio(1); _Pragma("unroll") for (int m = 0; m < 4; ++m) _Pragma("unroll") for (int n = 0; n < 2; ++n) _Pragma("unroll") for (int k = 0; k < 2; ++k) \
;         acc[ai][bj][m][n] = __builtin_amdgcn_mfma_f32_16x16x32_bf16(Bt[n][k], At[m][k], acc[ai][bj][m][n], 0, 0, 0); __builtin_amdgcn_s_setprio(0); } while (0)
;     __device__ __forceinline__ void operator()(const f32x4 (&acc)[2][2][4][2], const Unit& u, int wr, int wc, int fr, int fq) const {
;     ...
;             for (int m = 0; m < 4; ++m) { const size_t row = (size_t)u.pm * BM + ai * HALF + wr * 64 + m * 16 + fr;
;                 const float rs = tab[ai * HALF + wr * 64 + m * 16 + fr];
;                 f32x4 h[2];
; #pragma unroll
;                 for (int n = 0; n < 2; ++n) { const f32x4 g = acc[ai][0][m][n] * rs, up = acc[ai][1][m][n] * rs;
; #pragma unroll
;                     for (int j = 0; j < 4; ++j) h[n][j] = g[j] * sigmoidf_(g[j]) * up[j]; }
;                 *(u32x4*)(H + row * 5632 + u.pn * HALF + wc * 32 + fq * 8) = pack8(h[0], h[1]); }
; template <class Epi, class Sched, bool ALIGN_EPI = false, bool SP2 = false>
; __device__ __forceinline__ void gemm_phase(PG8_LAS unsigned char* lds, const Gemm g, const Sched& S, const Epi& E) {
;     ...
;             PG8_LDA(At, 1, 1); PG8_STAGE(PG8_SB(1, 0), b3, voffB); PG8_STAGE(PG8_SB(1, 1), b3 + hstepB, voffB); PG8_STAGE(PG8_SA(1, 0), a3, voffA);
;             PG8_WAIT_V(8); PG8_WAIT_L(0); PG8_BAR; PG8_MMA(1, 0, At, B0); PG8_MMA(1, 1, At, B1); PG8_BAR; PG8_SCHED;
	s_setprio 1
	s_waitcnt lgkmcnt(0)
	s_setprio 0
	s_setprio 1
	s_setprio 0
	s_barrier
	s_add_i32 s38, s63, s4
	v_lshl_add_u64 v[216:217], v[216:217], 0, s[16:17]
	s_mov_b32 m0, s38
	ds_read_b128 v[184:187], v153 offset:49152
	ds_read_b128 v[188:191], v153 offset:50176
	ds_read_b128 v[192:195], v153 offset:51200
	ds_read_b128 v[196:199], v153 offset:52224
	ds_read_b128 v[200:203], v153 offset:53248
	ds_read_b128 v[204:207], v153 offset:54272
	ds_read_b128 v[208:211], v153 offset:55296
	ds_read_b128 v[212:215], v153 offset:56320
	global_load_lds_dwordx4 v[216:217], off
	s_add_i32 m0, s38, 0x2000
	s_add_u32 s34, s34, 0x80080
	v_lshl_add_u64 v[216:217], v[218:219], 0, s[16:17]
	s_addc_u32 s35, s35, 0
	s_add_i32 s38, s64, s4
	global_load_lds_dwordx4 v[216:217], off
	v_lshl_add_u64 v[216:217], s[34:35], 0, v[132:133]
	s_mov_b32 m0, s38
	s_nop 0
	global_load_lds_dwordx4 v[216:217], off
	v_lshl_add_u64 v[216:217], s[34:35], 0, v[128:129]
	s_add_i32 m0, s38, 0x2000
	s_nop 0
	global_load_lds_dwordx4 v[216:217], off
	v_lshl_add_u64 v[216:217], v[220:221], 0, s[16:17]
	s_mov_b32 m0, s46
	s_nop 0
	v_lshl_add_u64 v[216:217], v[222:223], 0, s[16:17]
	s_mov_b32 m0, s47
	s_nop 0
	s_waitcnt vmcnt(6)
	s_waitcnt lgkmcnt(0)
	s_barrier
	s_setprio 1
	s_waitcnt lgkmcnt(0)
	v_mfma_f32_16x16x32_bf16 v[60:63], v[144:147], v[184:187], v[60:63]
	v_mfma_f32_16x16x32_bf16 v[52:55], v[160:163], v[184:187], v[52:55]
	v_mfma_f32_16x16x32_bf16 v[44:47], v[144:147], v[192:195], v[44:47]
	v_mfma_f32_16x16x32_bf16 v[36:39], v[160:163], v[192:195], v[36:39]
	v_mfma_f32_16x16x32_bf16 v[28:31], v[144:147], v[200:203], v[28:31]
	v_mfma_f32_16x16x32_bf16 v[20:23], v[160:163], v[200:203], v[20:23]
	v_mfma_f32_16x16x32_bf16 v[12:15], v[144:147], v[208:211], v[12:15]
	v_mfma_f32_16x16x32_bf16 v[4:7], v[160:163], v[208:211], v[4:7]
	v_mfma_f32_16x16x32_bf16 v[60:63], v[156:159], v[188:191], v[60:63]
	v_mfma_f32_16x16x32_bf16 v[52:55], v[164:167], v[188:191], v[52:55]
	v_mfma_f32_16x16x32_bf16 v[44:47], v[156:159], v[196:199], v[44:47]
	v_mfma_f32_16x16x32_bf16 v[36:39], v[164:167], v[196:199], v[36:39]
	v_mfma_f32_16x16x32_bf16 v[28:31], v[156:159], v[204:207], v[28:31]
	v_mfma_f32_16x16x32_bf16 v[20:23], v[164:167], v[204:207], v[20:23]
	v_mfma_f32_16x16x32_bf16 v[12:15], v[156:159], v[212:215], v[12:15]
	v_mfma_f32_16x16x32_bf16 v[4:7], v[164:167], v[212:215], v[4:7]
	s_setprio 0
	s_setprio 1
	v_mfma_f32_16x16x32_bf16 v[56:59], v[168:171], v[184:187], v[56:59]
	v_mfma_f32_16x16x32_bf16 v[48:51], v[176:179], v[184:187], v[48:51]
	v_mfma_f32_16x16x32_bf16 v[40:43], v[168:171], v[192:195], v[40:43]
	v_mfma_f32_16x16x32_bf16 v[32:35], v[176:179], v[192:195], v[32:35]
	v_mfma_f32_16x16x32_bf16 v[24:27], v[168:171], v[200:203], v[24:27]
	v_mfma_f32_16x16x32_bf16 v[16:19], v[176:179], v[200:203], v[16:19]
	v_mfma_f32_16x16x32_bf16 v[8:11], v[168:171], v[208:211], v[8:11]
	v_mfma_f32_16x16x32_bf16 v[0:3], v[176:179], v[208:211], v[0:3]
	v_mfma_f32_16x16x32_bf16 v[56:59], v[172:175], v[188:191], v[56:59]
	v_mfma_f32_16x16x32_bf16 v[48:51], v[180:183], v[188:191], v[48:51]
	v_mfma_f32_16x16x32_bf16 v[40:43], v[172:175], v[196:199], v[40:43]
	v_mfma_f32_16x16x32_bf16 v[32:35], v[180:183], v[196:199], v[32:35]
	v_mfma_f32_16x16x32_bf16 v[24:27], v[172:175], v[204:207], v[24:27]
	v_mfma_f32_16x16x32_bf16 v[16:19], v[180:183], v[204:207], v[16:19]
	v_mfma_f32_16x16x32_bf16 v[8:11], v[172:175], v[212:215], v[8:11]
	v_mfma_f32_16x16x32_bf16 v[0:3], v[180:183], v[212:215], v[0:3]
	s_setprio 0
	s_barrier
	s_add_i32 s62, s62, 2
	s_add_u32 s30, s30, 0x100
	s_addc_u32 s31, s31, 0
	s_add_u32 s60, s60, 0x100
	s_addc_u32 s61, s61, 0
	s_cmp_gt_u32 s62, 29
	s_cbranch_scc0 .Lp7h_loop
	s_branch .Lp7_after_loop
.Lp7_h_epi:
	s_lshl_b32 s20, s58, 7
	s_ashr_i32 s21, s20, 31
	v_ashrrev_i32_e32 v145, 31, v144
	v_mov_b64_e32 v[112:113], s[44:45]
	v_mad_u64_u32 v[112:113], s[30:31], v146, s56, v[112:113]
	v_mad_i32_i24 v113, v147, s56, v113
	v_lshl_add_u64 v[112:113], s[20:21], 1, v[112:113]
	v_lshl_add_u64 v[112:113], v[112:113], 0, s[12:13]
	v_lshl_add_u64 v[112:113], v[144:145], 1, v[112:113]
	s_cmp_lt_u32 s72, 128
	s_cbranch_scc0 .Lp7_h_epi2
	s_mov_b32 s20, 0xffea0000
	s_mov_b32 s21, -1
	v_lshl_add_u64 v[112:113], v[112:113], 0, s[20:21]
	v_add_u32_e32 v155, 0xfffffe00, v155
.Lp7_h_epi2:
	s_mov_b32 s20, 0x160000
	s_branch .Lp7_blk4
